# P5 s5c: U sub-chunk loads merged with table loads; GELU epilogue U loads prefetched
# speedup vs baseline: 1.0205x; 1.0072x over previous
.LBB0_1085:
	s_or_b64 exec, exec, s[6:7]
	s_load_dwordx2 s[6:7], s[52:53], 0xa8
	v_mov_b32_e32 v141, v121
	v_lshlrev_b32_e32 v120, 2, v155
	v_lshlrev_b64 v[4:5], 11, v[148:149]
	v_lshl_add_u64 v[10:11], v[150:151], 0, v[140:141]
	s_waitcnt lgkmcnt(0)
	v_lshl_add_u64 v[6:7], s[6:7], 0, v[120:121]
	v_lshl_add_u64 v[28:29], v[10:11], 0, v[4:5]
	v_lshl_add_u64 v[8:9], v[6:7], 0, v[140:141]
	global_load_dwordx4 v[12:15], v[28:29], off
	global_load_dwordx4 v[4:7], v[8:9], off
	v_lshlrev_b64 v[64:65], 11, v[146:147]
	v_lshl_add_u64 v[64:65], v[10:11], 0, v[64:65]
	global_load_dwordx4 v[52:55], v[64:65], off
	v_lshlrev_b64 v[64:65], 11, v[144:145]
	v_lshl_add_u64 v[64:65], v[10:11], 0, v[64:65]
	global_load_dwordx4 v[56:59], v[64:65], off
	v_lshlrev_b64 v[64:65], 11, v[142:143]
	v_lshl_add_u64 v[64:65], v[10:11], 0, v[64:65]
	global_load_dwordx4 v[60:63], v[64:65], off
	v_lshlrev_b64 v[8:9], 11, v[146:147]
	v_lshlrev_b32_e32 v120, 1, v155
	v_lshlrev_b64 v[28:29], 10, v[148:149]
	v_lshl_add_u64 v[30:31], v[10:11], 0, v[8:9]
	v_lshl_add_u64 v[8:9], v[134:135], 0, v[120:121]
	v_lshl_add_u64 v[28:29], v[8:9], 0, v[28:29]
	v_add_u32_e32 v133, s44, v133
	v_add_u16_e32 v178, s44, v178
	s_waitcnt vmcnt(3)
	v_pk_fma_f32 v[12:13], v[4:5], v[12:13], v[24:25]
	s_nop 0
	v_mul_f32_e32 v24, 0x3d372713, v12
	v_mul_f32_e32 v25, 0x3d372713, v13
	v_pk_fma_f32 v[14:15], v[6:7], v[14:15], v[26:27]
	v_mul_f32_e32 v24, v12, v24
	v_mul_f32_e32 v25, v13, v25
	v_mul_f32_e32 v26, 0x3d372713, v14
	v_mul_f32_e32 v27, 0x3d372713, v15
	v_fma_f32 v24, v12, v24, v12
	v_fma_f32 v25, v13, v25, v13
	v_mul_f32_e32 v26, v14, v26
	v_mul_f32_e32 v27, v15, v27
	v_mul_f32_e32 v24, 0x3f4c422a, v24
	v_mul_f32_e32 v25, 0x3f4c422a, v25
	v_fma_f32 v26, v14, v26, v14
	v_fma_f32 v27, v15, v27, v15
	v_add_f32_e32 v24, v24, v24
	v_add_f32_e32 v25, v25, v25
	v_mul_f32_e32 v26, 0x3f4c422a, v26
	v_mul_f32_e32 v27, 0x3f4c422a, v27
	v_mul_f32_e32 v24, 0x3fb8aa3b, v24
	v_mul_f32_e32 v25, 0x3fb8aa3b, v25
	v_add_f32_e32 v26, v26, v26
	v_add_f32_e32 v27, v27, v27
	v_exp_f32_e32 v24, v24
	v_exp_f32_e32 v25, v25
	v_mul_f32_e32 v26, 0x3fb8aa3b, v26
	v_mul_f32_e32 v27, 0x3fb8aa3b, v27
	v_exp_f32_e32 v26, v26
	v_exp_f32_e32 v27, v27
	v_pk_add_f32 v[24:25], v[24:25], 1.0 op_sel_hi:[1,0]
	v_pk_mul_f32 v[12:13], v[12:13], 0.5 op_sel_hi:[1,0]
	v_div_scale_f32 v32, s[6:7], v25, v25, 2.0
	v_pk_add_f32 v[26:27], v[26:27], 1.0 op_sel_hi:[1,0]
	v_div_scale_f32 v34, s[6:7], v24, v24, 2.0
	v_rcp_f32_e32 v40, v32
	v_div_scale_f32 v36, s[8:9], v27, v27, 2.0
	v_rcp_f32_e32 v41, v34
	v_div_scale_f32 v38, s[10:11], v26, v26, 2.0
	v_rcp_f32_e32 v42, v36
	v_rcp_f32_e32 v43, v38
	v_fma_f32 v44, -v32, v40, 1.0
	v_div_scale_f32 v33, vcc, 2.0, v25, 2.0
	v_fma_f32 v45, -v34, v41, 1.0
	v_fmac_f32_e32 v40, v44, v40
	v_div_scale_f32 v35, s[6:7], 2.0, v24, 2.0
	v_fma_f32 v46, -v36, v42, 1.0
	v_fmac_f32_e32 v41, v45, v41
	v_mul_f32_e32 v44, v33, v40
	v_div_scale_f32 v37, s[8:9], 2.0, v27, 2.0
	v_fma_f32 v47, -v38, v43, 1.0
	v_fmac_f32_e32 v42, v46, v42
	v_mul_f32_e32 v45, v35, v41
	v_fma_f32 v48, -v32, v44, v33
	v_div_scale_f32 v39, s[10:11], 2.0, v26, 2.0
	v_fmac_f32_e32 v43, v47, v43
	v_mul_f32_e32 v46, v37, v42
	v_fma_f32 v49, -v34, v45, v35
	v_fmac_f32_e32 v44, v48, v40
	v_mul_f32_e32 v47, v39, v43
	v_fma_f32 v50, -v36, v46, v37
	v_fmac_f32_e32 v45, v49, v41
	v_fma_f32 v32, -v32, v44, v33
	v_fma_f32 v51, -v38, v47, v39
	v_fmac_f32_e32 v46, v50, v42
	v_fma_f32 v33, -v34, v45, v35
	v_div_fmas_f32 v32, v32, v40, v44
	s_mov_b64 vcc, s[6:7]
	v_fmac_f32_e32 v47, v51, v43
	v_fma_f32 v34, -v36, v46, v37
	v_div_fixup_f32 v25, v32, v25, 2.0
	v_div_fmas_f32 v32, v33, v41, v45
	s_mov_b64 vcc, s[8:9]
	v_fma_f32 v35, -v38, v47, v39
	v_div_fixup_f32 v24, v32, v24, 2.0
	v_div_fmas_f32 v32, v34, v42, v46
	s_mov_b64 vcc, s[10:11]
	v_pk_add_f32 v[24:25], v[24:25], 1.0 op_sel_hi:[1,0] neg_lo:[1,0] neg_hi:[1,0]
	v_div_fixup_f32 v27, v32, v27, 2.0
	v_div_fmas_f32 v32, v35, v43, v47
	v_pk_add_f32 v[24:25], v[24:25], 1.0 op_sel_hi:[1,0]
	v_div_fixup_f32 v26, v32, v26, 2.0
	v_pk_mul_f32 v[12:13], v[12:13], v[24:25]
	v_pk_add_f32 v[24:25], v[26:27], 1.0 op_sel_hi:[1,0] neg_lo:[1,0] neg_hi:[1,0]
	v_pk_mul_f32 v[14:15], v[14:15], 0.5 op_sel_hi:[1,0]
	v_pk_add_f32 v[24:25], v[24:25], 1.0 op_sel_hi:[1,0]
	v_cvt_pk_bf16_f32 v12, v12, v13
	v_pk_mul_f32 v[14:15], v[14:15], v[24:25]
	v_lshlrev_b64 v[24:25], 10, v[146:147]
	v_cvt_pk_bf16_f32 v13, v14, v15
	global_store_dwordx2 v[28:29], v[12:13], off
	v_lshlrev_b64 v[26:27], 11, v[144:145]
	v_lshl_add_u64 v[24:25], v[8:9], 0, v[24:25]
	v_lshl_add_u64 v[26:27], v[10:11], 0, v[26:27]
	s_waitcnt vmcnt(3)
	v_mov_b64_e32 v[12:13], v[52:53]
	v_mov_b64_e32 v[14:15], v[54:55]
	v_pk_fma_f32 v[12:13], v[4:5], v[12:13], v[20:21]
	s_nop 0
	v_mul_f32_e32 v20, 0x3d372713, v12
	v_mul_f32_e32 v21, 0x3d372713, v13
	v_pk_fma_f32 v[14:15], v[6:7], v[14:15], v[22:23]
	v_mul_f32_e32 v20, v12, v20
	v_mul_f32_e32 v21, v13, v21
	v_mul_f32_e32 v22, 0x3d372713, v14
	v_mul_f32_e32 v23, 0x3d372713, v15
	v_fma_f32 v20, v12, v20, v12
	v_fma_f32 v21, v13, v21, v13
	v_mul_f32_e32 v22, v14, v22
	v_mul_f32_e32 v23, v15, v23
	v_mul_f32_e32 v20, 0x3f4c422a, v20
	v_mul_f32_e32 v21, 0x3f4c422a, v21
	v_fma_f32 v22, v14, v22, v14
	v_fma_f32 v23, v15, v23, v15
	v_add_f32_e32 v20, v20, v20
	v_add_f32_e32 v21, v21, v21
	v_mul_f32_e32 v22, 0x3f4c422a, v22
	v_mul_f32_e32 v23, 0x3f4c422a, v23
	v_mul_f32_e32 v20, 0x3fb8aa3b, v20
	v_mul_f32_e32 v21, 0x3fb8aa3b, v21
	v_add_f32_e32 v22, v22, v22
	v_add_f32_e32 v23, v23, v23
	v_exp_f32_e32 v20, v20
	v_exp_f32_e32 v21, v21
	v_mul_f32_e32 v22, 0x3fb8aa3b, v22
	v_mul_f32_e32 v23, 0x3fb8aa3b, v23
	v_exp_f32_e32 v22, v22
	v_exp_f32_e32 v23, v23
	v_pk_add_f32 v[20:21], v[20:21], 1.0 op_sel_hi:[1,0]
	v_pk_mul_f32 v[12:13], v[12:13], 0.5 op_sel_hi:[1,0]
	v_div_scale_f32 v28, s[6:7], v21, v21, 2.0
	v_pk_add_f32 v[22:23], v[22:23], 1.0 op_sel_hi:[1,0]
	v_div_scale_f32 v30, s[6:7], v20, v20, 2.0
	v_rcp_f32_e32 v36, v28
	v_div_scale_f32 v32, s[8:9], v23, v23, 2.0
	v_rcp_f32_e32 v37, v30
	v_div_scale_f32 v34, s[10:11], v22, v22, 2.0
	v_rcp_f32_e32 v38, v32
	v_rcp_f32_e32 v39, v34
	v_fma_f32 v40, -v28, v36, 1.0
	v_div_scale_f32 v29, vcc, 2.0, v21, 2.0
	v_fma_f32 v41, -v30, v37, 1.0
	v_fmac_f32_e32 v36, v40, v36
	v_div_scale_f32 v31, s[6:7], 2.0, v20, 2.0
	v_fma_f32 v42, -v32, v38, 1.0
	v_fmac_f32_e32 v37, v41, v37
	v_mul_f32_e32 v40, v29, v36
	v_div_scale_f32 v33, s[8:9], 2.0, v23, 2.0
	v_fma_f32 v43, -v34, v39, 1.0
	v_fmac_f32_e32 v38, v42, v38
	v_mul_f32_e32 v41, v31, v37
	v_fma_f32 v44, -v28, v40, v29
	v_div_scale_f32 v35, s[10:11], 2.0, v22, 2.0
	v_fmac_f32_e32 v39, v43, v39
	v_mul_f32_e32 v42, v33, v38
	v_fma_f32 v45, -v30, v41, v31
	v_fmac_f32_e32 v40, v44, v36
	v_mul_f32_e32 v43, v35, v39
	v_fma_f32 v46, -v32, v42, v33
	v_fmac_f32_e32 v41, v45, v37
	v_fma_f32 v28, -v28, v40, v29
	v_fma_f32 v47, -v34, v43, v35
	v_fmac_f32_e32 v42, v46, v38
	v_fma_f32 v29, -v30, v41, v31
	v_div_fmas_f32 v28, v28, v36, v40
	s_mov_b64 vcc, s[6:7]
	v_fmac_f32_e32 v43, v47, v39
	v_fma_f32 v30, -v32, v42, v33
	v_div_fixup_f32 v21, v28, v21, 2.0
	v_div_fmas_f32 v28, v29, v37, v41
	s_mov_b64 vcc, s[8:9]
	v_fma_f32 v31, -v34, v43, v35
	v_div_fixup_f32 v20, v28, v20, 2.0
	v_div_fmas_f32 v28, v30, v38, v42
	s_mov_b64 vcc, s[10:11]
	v_pk_add_f32 v[20:21], v[20:21], 1.0 op_sel_hi:[1,0] neg_lo:[1,0] neg_hi:[1,0]
	v_div_fixup_f32 v23, v28, v23, 2.0
	v_div_fmas_f32 v28, v31, v39, v43
	v_pk_add_f32 v[20:21], v[20:21], 1.0 op_sel_hi:[1,0]
	v_div_fixup_f32 v22, v28, v22, 2.0
	v_pk_mul_f32 v[12:13], v[12:13], v[20:21]
	v_pk_add_f32 v[20:21], v[22:23], 1.0 op_sel_hi:[1,0] neg_lo:[1,0] neg_hi:[1,0]
	v_pk_mul_f32 v[14:15], v[14:15], 0.5 op_sel_hi:[1,0]
	v_pk_add_f32 v[20:21], v[20:21], 1.0 op_sel_hi:[1,0]
	v_cvt_pk_bf16_f32 v12, v12, v13
	v_pk_mul_f32 v[14:15], v[14:15], v[20:21]
	v_lshlrev_b64 v[22:23], 11, v[142:143]
	v_cvt_pk_bf16_f32 v13, v14, v15
	global_store_dwordx2 v[24:25], v[12:13], off
	v_lshl_add_u64 v[10:11], v[10:11], 0, v[22:23]
	v_lshlrev_b64 v[20:21], 10, v[144:145]
	v_lshl_add_u64 v[20:21], v[8:9], 0, v[20:21]
	s_waitcnt vmcnt(3)
	v_mov_b64_e32 v[12:13], v[56:57]
	v_mov_b64_e32 v[14:15], v[58:59]
	v_pk_fma_f32 v[12:13], v[4:5], v[12:13], v[16:17]
	s_nop 0
	v_mul_f32_e32 v16, 0x3d372713, v12
	v_mul_f32_e32 v17, 0x3d372713, v13
	v_pk_fma_f32 v[14:15], v[6:7], v[14:15], v[18:19]
	v_mul_f32_e32 v16, v12, v16
	v_mul_f32_e32 v17, v13, v17
	v_mul_f32_e32 v18, 0x3d372713, v14
	v_mul_f32_e32 v19, 0x3d372713, v15
	v_fma_f32 v16, v12, v16, v12
	v_fma_f32 v17, v13, v17, v13
	v_mul_f32_e32 v18, v14, v18
	v_mul_f32_e32 v19, v15, v19
	v_mul_f32_e32 v16, 0x3f4c422a, v16
	v_mul_f32_e32 v17, 0x3f4c422a, v17
	v_fma_f32 v18, v14, v18, v14
	v_fma_f32 v19, v15, v19, v15
	v_add_f32_e32 v16, v16, v16
	v_add_f32_e32 v17, v17, v17
	v_mul_f32_e32 v18, 0x3f4c422a, v18
	v_mul_f32_e32 v19, 0x3f4c422a, v19
	v_mul_f32_e32 v16, 0x3fb8aa3b, v16
	v_mul_f32_e32 v17, 0x3fb8aa3b, v17
	v_add_f32_e32 v18, v18, v18
	v_add_f32_e32 v19, v19, v19
	v_exp_f32_e32 v16, v16
	v_exp_f32_e32 v17, v17
	v_mul_f32_e32 v18, 0x3fb8aa3b, v18
	v_mul_f32_e32 v19, 0x3fb8aa3b, v19
	v_exp_f32_e32 v18, v18
	v_exp_f32_e32 v19, v19
	v_pk_add_f32 v[16:17], v[16:17], 1.0 op_sel_hi:[1,0]
	v_pk_mul_f32 v[12:13], v[12:13], 0.5 op_sel_hi:[1,0]
	v_div_scale_f32 v22, s[6:7], v17, v17, 2.0
	v_pk_add_f32 v[18:19], v[18:19], 1.0 op_sel_hi:[1,0]
	v_div_scale_f32 v24, s[6:7], v16, v16, 2.0
	v_rcp_f32_e32 v30, v22
	v_div_scale_f32 v26, s[8:9], v19, v19, 2.0
	v_rcp_f32_e32 v31, v24
	v_div_scale_f32 v28, s[10:11], v18, v18, 2.0
	v_rcp_f32_e32 v32, v26
	v_rcp_f32_e32 v33, v28
	v_fma_f32 v34, -v22, v30, 1.0
	v_div_scale_f32 v23, vcc, 2.0, v17, 2.0
	v_fma_f32 v35, -v24, v31, 1.0
	v_fmac_f32_e32 v30, v34, v30
	v_div_scale_f32 v25, s[6:7], 2.0, v16, 2.0
	v_fma_f32 v36, -v26, v32, 1.0
	v_fmac_f32_e32 v31, v35, v31
	v_mul_f32_e32 v34, v23, v30
	v_div_scale_f32 v27, s[8:9], 2.0, v19, 2.0
	v_fma_f32 v37, -v28, v33, 1.0
	v_fmac_f32_e32 v32, v36, v32
	v_mul_f32_e32 v35, v25, v31
	v_fma_f32 v38, -v22, v34, v23
	v_div_scale_f32 v29, s[10:11], 2.0, v18, 2.0
	v_fmac_f32_e32 v33, v37, v33
	v_mul_f32_e32 v36, v27, v32
	v_fma_f32 v39, -v24, v35, v25
	v_fmac_f32_e32 v34, v38, v30
	v_mul_f32_e32 v37, v29, v33
	v_fma_f32 v40, -v26, v36, v27
	v_fmac_f32_e32 v35, v39, v31
	v_fma_f32 v22, -v22, v34, v23
	v_fma_f32 v41, -v28, v37, v29
	v_fmac_f32_e32 v36, v40, v32
	v_fma_f32 v23, -v24, v35, v25
	v_div_fmas_f32 v22, v22, v30, v34
	s_mov_b64 vcc, s[6:7]
	v_fmac_f32_e32 v37, v41, v33
	v_fma_f32 v24, -v26, v36, v27
	v_div_fixup_f32 v17, v22, v17, 2.0
	v_div_fmas_f32 v22, v23, v31, v35
	s_mov_b64 vcc, s[8:9]
	v_fma_f32 v25, -v28, v37, v29
	v_div_fixup_f32 v16, v22, v16, 2.0
	v_div_fmas_f32 v22, v24, v32, v36
	s_mov_b64 vcc, s[10:11]
	v_pk_add_f32 v[16:17], v[16:17], 1.0 op_sel_hi:[1,0] neg_lo:[1,0] neg_hi:[1,0]
	v_div_fixup_f32 v19, v22, v19, 2.0
	v_div_fmas_f32 v22, v25, v33, v37
	v_pk_add_f32 v[16:17], v[16:17], 1.0 op_sel_hi:[1,0]
	v_div_fixup_f32 v18, v22, v18, 2.0
	v_pk_mul_f32 v[12:13], v[12:13], v[16:17]
	v_pk_add_f32 v[16:17], v[18:19], 1.0 op_sel_hi:[1,0] neg_lo:[1,0] neg_hi:[1,0]
	v_pk_mul_f32 v[14:15], v[14:15], 0.5 op_sel_hi:[1,0]
	v_pk_add_f32 v[16:17], v[16:17], 1.0 op_sel_hi:[1,0]
	v_cvt_pk_bf16_f32 v12, v12, v13
	v_pk_mul_f32 v[14:15], v[14:15], v[16:17]
	v_cmp_lt_i32_e32 vcc, s47, v133
	v_cvt_pk_bf16_f32 v13, v14, v15
	global_store_dwordx2 v[20:21], v[12:13], off
	v_lshlrev_b64 v[14:15], 10, v[142:143]
	v_lshl_add_u64 v[8:9], v[8:9], 0, v[14:15]
	s_or_b64 s[60:61], vcc, s[60:61]
	s_waitcnt vmcnt(3)
	v_mov_b64_e32 v[10:11], v[60:61]
	v_mov_b64_e32 v[12:13], v[62:63]
	v_pk_fma_f32 v[0:1], v[4:5], v[10:11], v[0:1]
	s_nop 0
	v_mul_f32_e32 v4, 0x3d372713, v0
	v_mul_f32_e32 v5, 0x3d372713, v1
	v_pk_fma_f32 v[2:3], v[6:7], v[12:13], v[2:3]
	v_mul_f32_e32 v4, v0, v4
	v_mul_f32_e32 v5, v1, v5
	v_mul_f32_e32 v6, 0x3d372713, v2
	v_mul_f32_e32 v7, 0x3d372713, v3
	v_fma_f32 v4, v0, v4, v0
	v_fma_f32 v5, v1, v5, v1
	v_mul_f32_e32 v6, v2, v6
	v_mul_f32_e32 v7, v3, v7
	v_mul_f32_e32 v4, 0x3f4c422a, v4
	v_mul_f32_e32 v5, 0x3f4c422a, v5
	v_fma_f32 v6, v2, v6, v2
	v_fma_f32 v7, v3, v7, v3
	v_add_f32_e32 v4, v4, v4
	v_add_f32_e32 v5, v5, v5
	v_mul_f32_e32 v6, 0x3f4c422a, v6
	v_mul_f32_e32 v7, 0x3f4c422a, v7
	v_mul_f32_e32 v4, 0x3fb8aa3b, v4
	v_mul_f32_e32 v5, 0x3fb8aa3b, v5
	v_add_f32_e32 v6, v6, v6
	v_add_f32_e32 v7, v7, v7
	v_exp_f32_e32 v4, v4
	v_exp_f32_e32 v5, v5
	v_mul_f32_e32 v6, 0x3fb8aa3b, v6
	v_mul_f32_e32 v7, 0x3fb8aa3b, v7
	v_exp_f32_e32 v6, v6
	v_exp_f32_e32 v7, v7
	v_pk_add_f32 v[4:5], v[4:5], 1.0 op_sel_hi:[1,0]
	v_pk_mul_f32 v[0:1], v[0:1], 0.5 op_sel_hi:[1,0]
	v_div_scale_f32 v10, s[6:7], v5, v5, 2.0
	v_pk_add_f32 v[6:7], v[6:7], 1.0 op_sel_hi:[1,0]
	v_div_scale_f32 v12, s[6:7], v4, v4, 2.0
	v_rcp_f32_e32 v18, v10
	v_div_scale_f32 v14, s[8:9], v7, v7, 2.0
	v_rcp_f32_e32 v19, v12
	v_div_scale_f32 v16, s[10:11], v6, v6, 2.0
	v_rcp_f32_e32 v20, v14
	v_rcp_f32_e32 v21, v16
	v_fma_f32 v22, -v10, v18, 1.0
	v_div_scale_f32 v11, vcc, 2.0, v5, 2.0
	v_fma_f32 v23, -v12, v19, 1.0
	v_fmac_f32_e32 v18, v22, v18
	v_div_scale_f32 v13, s[6:7], 2.0, v4, 2.0
	v_fma_f32 v24, -v14, v20, 1.0
	v_fmac_f32_e32 v19, v23, v19
	v_mul_f32_e32 v22, v11, v18
	v_div_scale_f32 v15, s[8:9], 2.0, v7, 2.0
	v_fma_f32 v25, -v16, v21, 1.0
	v_fmac_f32_e32 v20, v24, v20
	v_mul_f32_e32 v23, v13, v19
	v_fma_f32 v26, -v10, v22, v11
	v_div_scale_f32 v17, s[10:11], 2.0, v6, 2.0
	v_fmac_f32_e32 v21, v25, v21
	v_mul_f32_e32 v24, v15, v20
	v_fma_f32 v27, -v12, v23, v13
	v_fmac_f32_e32 v22, v26, v18
	v_mul_f32_e32 v25, v17, v21
	v_fma_f32 v28, -v14, v24, v15
	v_fmac_f32_e32 v23, v27, v19
	v_fma_f32 v10, -v10, v22, v11
	v_fma_f32 v29, -v16, v25, v17
	v_fmac_f32_e32 v24, v28, v20
	v_fma_f32 v11, -v12, v23, v13
	v_div_fmas_f32 v10, v10, v18, v22
	s_mov_b64 vcc, s[6:7]
	v_fmac_f32_e32 v25, v29, v21
	v_fma_f32 v12, -v14, v24, v15
	v_div_fixup_f32 v5, v10, v5, 2.0
	v_div_fmas_f32 v10, v11, v19, v23
	s_mov_b64 vcc, s[8:9]
	v_fma_f32 v13, -v16, v25, v17
	v_div_fixup_f32 v4, v10, v4, 2.0
	v_div_fmas_f32 v10, v12, v20, v24
	s_mov_b64 vcc, s[10:11]
	v_pk_add_f32 v[4:5], v[4:5], 1.0 op_sel_hi:[1,0] neg_lo:[1,0] neg_hi:[1,0]
	v_div_fixup_f32 v7, v10, v7, 2.0
	v_div_fmas_f32 v10, v13, v21, v25
	v_pk_add_f32 v[4:5], v[4:5], 1.0 op_sel_hi:[1,0]
	v_div_fixup_f32 v6, v10, v6, 2.0
	v_pk_mul_f32 v[0:1], v[0:1], v[4:5]
	v_pk_add_f32 v[4:5], v[6:7], 1.0 op_sel_hi:[1,0] neg_lo:[1,0] neg_hi:[1,0]
	v_pk_mul_f32 v[2:3], v[2:3], 0.5 op_sel_hi:[1,0]
	v_pk_add_f32 v[4:5], v[4:5], 1.0 op_sel_hi:[1,0]
	v_cvt_pk_bf16_f32 v0, v0, v1
	v_pk_mul_f32 v[2:3], v[2:3], v[4:5]
	s_nop 0
	v_cvt_pk_bf16_f32 v1, v2, v3
	global_store_dwordx2 v[8:9], v[0:1], off
	s_andn2_b64 exec, exec, s[60:61]
	s_cbranch_execz .LBB0_1118
.LBB0_1086:
	v_ashrrev_i32_e32 v0, 5, v133
	v_cmp_lt_i32_e64 s[6:7], 63, v0
	v_cmp_gt_i32_e32 vcc, 64, v0
	s_and_saveexec_b64 s[8:9], vcc
	s_xor_b64 s[8:9], exec, s[8:9]
	v_ashrrev_i32_e32 v152, 7, v133
	v_bfe_u32 v141, v133, 5, 2
	v_and_b32_e32 v154, -4, v0
	s_or_saveexec_b64 s[8:9], s[8:9]
	v_mov_b32_e32 v181, 4
	s_xor_b64 exec, exec, s[8:9]
	v_subrev_u32_e32 v1, 64, v0
	v_lshrrev_b32_e32 v152, 5, v1
	v_and_b32_e32 v1, 0xffffffe0, v1
	v_bfe_u32 v141, v133, 5, 5
	v_add_u32_e32 v154, 64, v1
	v_mov_b32_e32 v181, 32
	s_or_b64 exec, exec, s[8:9]
	v_and_b32_e32 v183, 31, v133
	v_lshlrev_b32_e32 v120, 6, v183
	v_lshl_or_b32 v148, v0, 6, v177
	v_lshl_add_u64 v[150:151], s[56:57], 0, v[120:121]
	v_lshl_add_u64 v[0:1], v[150:151], 0, v[138:139]
	v_ashrrev_i32_e32 v149, 31, v148
	v_or_b32_e32 v146, 16, v148
	v_or_b32_e32 v144, 32, v148
	v_or_b32_e32 v142, 48, v148
	v_ashrrev_i32_e32 v147, 31, v146
	v_ashrrev_i32_e32 v145, 31, v144
	v_ashrrev_i32_e32 v143, 31, v142
	v_mov_b32_e32 v48, 0
	v_mov_b32_e32 v49, 0
	v_mov_b32_e32 v50, 0
	v_mov_b32_e32 v51, 0
	v_mov_b32_e32 v24, 0
	v_mov_b32_e32 v25, 0
	v_mov_b32_e32 v26, 0
	v_mov_b32_e32 v27, 0
	v_mov_b32_e32 v28, 0
	v_mov_b32_e32 v29, 0
	v_mov_b32_e32 v30, 0
	v_mov_b32_e32 v31, 0
	v_mov_b32_e32 v20, 0
	v_mov_b32_e32 v21, 0
	v_mov_b32_e32 v22, 0
	v_mov_b32_e32 v23, 0
	s_and_saveexec_b64 s[8:9], s[4:5]
	s_cbranch_execz .Ls5c_u_skip
	v_lshlrev_b64 v[2:3], 11, v[148:149]
	v_lshl_add_u64 v[10:11], v[0:1], 0, v[2:3]
	global_load_dwordx4 v[184:187], v[10:11], off
	global_load_dwordx4 v[188:191], v[10:11], off offset:16
	v_lshlrev_b64 v[2:3], 11, v[146:147]
	v_lshl_add_u64 v[10:11], v[0:1], 0, v[2:3]
	global_load_dwordx4 v[192:195], v[10:11], off
	global_load_dwordx4 v[196:199], v[10:11], off offset:16
	v_lshlrev_b64 v[2:3], 11, v[144:145]
	v_lshl_add_u64 v[10:11], v[0:1], 0, v[2:3]
	global_load_dwordx4 v[200:203], v[10:11], off
	global_load_dwordx4 v[204:207], v[10:11], off offset:16
	v_lshlrev_b64 v[2:3], 11, v[142:143]
	v_lshl_add_u64 v[10:11], v[0:1], 0, v[2:3]
	global_load_dwordx4 v[208:211], v[10:11], off
	global_load_dwordx4 v[212:215], v[10:11], off offset:16
.Ls5c_u_skip:
	s_or_b64 exec, exec, s[8:9]
	v_lshlrev_b32_e32 v120, 13, v183
	v_lshl_or_b32 v2, v183, 10, v122
	v_lshl_add_u64 v[0:1], v[124:125], 0, v[120:121]
	global_load_dwordx4 v[84:87], v2, s[58:59]
	global_load_dwordx4 v[116:119], v[0:1], off
	global_load_dwordx4 v[112:115], v[0:1], off offset:1024
	global_load_dwordx4 v[108:111], v[0:1], off offset:2048
	v_add_co_u32_e32 v2, vcc, 0x1000, v0
	v_lshlrev_b32_e32 v120, 12, v183
	s_nop 0
	v_addc_co_u32_e32 v3, vcc, 0, v1, vcc
	global_load_dwordx4 v[104:107], v[0:1], off offset:3072
	global_load_dwordx4 v[100:103], v[2:3], off
	global_load_dwordx4 v[96:99], v[2:3], off offset:1024
	global_load_dwordx4 v[88:91], v[2:3], off offset:2048
	v_lshl_add_u64 v[0:1], v[126:127], 0, v[120:121]
	global_load_dwordx4 v[92:95], v[2:3], off offset:3072
	global_load_dwordx4 v[76:79], v[0:1], off
	global_load_dwordx4 v[80:83], v[0:1], off offset:1024
	global_load_dwordx4 v[68:71], v[0:1], off offset:2048
	v_or_b32_e32 v2, 32, v183
	v_lshlrev_b32_e32 v120, 13, v2
	v_lshl_or_b32 v3, v2, 10, v122
	global_load_dwordx4 v[72:75], v[0:1], off offset:3072
	global_load_dwordx4 v[16:19], v3, s[58:59]
	v_lshl_add_u64 v[0:1], v[124:125], 0, v[120:121]
	global_load_dwordx4 v[64:67], v[0:1], off
	global_load_dwordx4 v[60:63], v[0:1], off offset:1024
	global_load_dwordx4 v[56:59], v[0:1], off offset:2048
	global_load_dwordx4 v[52:55], v[0:1], off offset:3072
	v_add_co_u32_e32 v0, vcc, s45, v0
	v_lshlrev_b32_e32 v120, 12, v2
	s_nop 0
	v_addc_co_u32_e32 v1, vcc, 0, v1, vcc
	global_load_dwordx4 v[44:47], v[0:1], off
	global_load_dwordx4 v[40:43], v[0:1], off offset:1024
	global_load_dwordx4 v[36:39], v[0:1], off offset:2048
	global_load_dwordx4 v[32:35], v[0:1], off offset:3072
	v_lshl_add_u64 v[0:1], v[126:127], 0, v[120:121]
	global_load_dwordx4 v[8:11], v[0:1], off
	global_load_dwordx4 v[12:15], v[0:1], off offset:1024
	global_load_dwordx4 v[4:7], v[0:1], off offset:2048
	s_nop 0
	global_load_dwordx4 v[0:3], v[0:1], off offset:3072
	s_and_saveexec_b64 s[8:9], s[4:5]
	s_waitcnt vmcnt(26)
	v_cvt_pk_bf16_f32 v48, v184, v185
	v_cvt_pk_bf16_f32 v49, v186, v187
	v_cvt_pk_bf16_f32 v50, v188, v189
	v_cvt_pk_bf16_f32 v51, v190, v191
	v_cvt_pk_bf16_f32 v24, v192, v193
	v_cvt_pk_bf16_f32 v25, v194, v195
	v_cvt_pk_bf16_f32 v26, v196, v197
	v_cvt_pk_bf16_f32 v27, v198, v199
	v_cvt_pk_bf16_f32 v28, v200, v201
	v_cvt_pk_bf16_f32 v29, v202, v203
	v_cvt_pk_bf16_f32 v30, v204, v205
	v_cvt_pk_bf16_f32 v31, v206, v207
	v_cvt_pk_bf16_f32 v20, v208, v209
	v_cvt_pk_bf16_f32 v21, v210, v211
	v_cvt_pk_bf16_f32 v22, v212, v213
	v_cvt_pk_bf16_f32 v23, v214, v215
	s_or_b64 exec, exec, s[8:9]
	v_lshl_or_b32 v158, v152, 6, v183
	v_mov_b32_e32 v120, v121
	v_ashrrev_i32_e32 v159, 31, v158
	v_lshlrev_b32_e32 v156, 2, v132
	v_mov_b64_e32 v[160:161], v[120:121]
	s_and_saveexec_b64 s[8:9], s[6:7]
	s_cbranch_execz .LBB0_1100
	s_load_dwordx2 s[10:11], s[52:53], 0x20
	v_lshlrev_b64 v[152:153], 9, v[158:159]
	v_mov_b32_e32 v157, v121
	s_waitcnt lgkmcnt(0)
	v_lshl_add_u64 v[152:153], s[10:11], 0, v[152:153]
	v_lshl_add_u64 v[152:153], v[152:153], 0, v[156:157]
	global_load_dwordx2 v[152:153], v[152:153], off
	s_waitcnt vmcnt(0)
	v_pk_mov_b32 v[160:161], v[152:153], v[152:153] op_sel:[1,0]
